# in-proj GEMM loops: each staging register's next-slab global load is re-issued right after its ds_write (before the second barrier) instead of all 12 after it
# speedup vs baseline: 1.0548x; 1.0225x over previous
; template <bool VT>
; DI void gemm_mainloop(f32x4 (&acc)[8][4], const char* abase, const char* bbase, unsigned toff, u16* sA, u16* sB, int loff, int wm, int wn, int fr, int fq) {
;     ...
;     __syncthreads();
; #pragma unroll
;     for (int i = 0; i < 8; ++i) *(u32x4*)(sA + loff + i * 32 * GSTR) = ra[i];
; #pragma unroll
;     for (int i = 0; i < 4; ++i) *(u32x4*)(sB + loff + i * 32 * GSTR) = rb[i];
;     __syncthreads();
;     if (kt + 1 < 16) {
;       const int ko = (kt + 1) * 128;
; #pragma unroll
;       for (int i = 0; i < 8; ++i) ra[i] = __builtin_amdgcn_raw_buffer_load_b128(ra_rs, (int)toff, i * 65536 + ko, 0);
; #pragma unroll
;       for (int i = 0; i < 4; ++i) rb[i] = __builtin_amdgcn_raw_buffer_load_b128(rb_rs, (int)toff, i * 65536 + ko, 0);
;     }
.LBB0_116:
	s_cmp_eq_u32 s6, 0x70800
	s_barrier
	s_cbranch_scc1 .Lw_last_nv
	s_add_i32 s7, s6, 0xfff90000
	s_add_i32 s36, s6, 0xfffa0000
	s_add_i32 s37, s6, 0xfffb0000
	s_add_i32 s38, s6, 0xfffc0000
	s_add_i32 s39, s6, 0xfffd0000
	s_add_i32 s98, s6, 0xfffe0000
	s_add_i32 s99, s6, 0xffff0000
	s_mov_b32 s87, s67
	s_waitcnt vmcnt(11)
	ds_write_b128 v180, v[130:133]
	buffer_load_dwordx4 v[130:133], v0, s[64:67], s7 offen
	s_waitcnt vmcnt(11)
	ds_write_b128 v180, v[134:137] offset:10240
	buffer_load_dwordx4 v[134:137], v0, s[64:67], s37 offen
	s_waitcnt vmcnt(11)
	ds_write_b128 v180, v[150:153] offset:25600
	buffer_load_dwordx4 v[150:153], v0, s[64:67], s98 offen
	s_waitcnt vmcnt(11)
	ds_write_b128 v180, v[138:141] offset:5120
	buffer_load_dwordx4 v[138:141], v0, s[64:67], s36 offen
	s_waitcnt vmcnt(11)
	ds_write_b128 v180, v[142:145] offset:15360
	buffer_load_dwordx4 v[142:145], v0, s[64:67], s38 offen
	s_waitcnt vmcnt(11)
	ds_write_b128 v180, v[154:157] offset:30720
	buffer_load_dwordx4 v[154:157], v0, s[64:67], s99 offen
	s_waitcnt vmcnt(11)
	ds_write_b128 v180, v[146:149] offset:20480
	buffer_load_dwordx4 v[146:149], v0, s[64:67], s39 offen
	s_waitcnt vmcnt(11)
	ds_write_b128 v180, v[158:161] offset:35840
	buffer_load_dwordx4 v[158:161], v0, s[64:67], s6 offen
	s_waitcnt vmcnt(11)
	ds_write_b128 v180, v[162:165] offset:40960
	buffer_load_dwordx4 v[162:165], v0, s[84:87], s7 offen
	s_waitcnt vmcnt(11)
	ds_write_b128 v180, v[166:169] offset:51200
	buffer_load_dwordx4 v[166:169], v0, s[84:87], s37 offen
	s_waitcnt vmcnt(11)
	ds_write_b128 v180, v[170:173] offset:46080
	buffer_load_dwordx4 v[170:173], v0, s[84:87], s36 offen
	s_waitcnt vmcnt(11)
	ds_write_b128 v180, v[174:177] offset:56320
	buffer_load_dwordx4 v[174:177], v0, s[84:87], s38 offen
	s_waitcnt lgkmcnt(0)
	s_barrier
	s_branch .LBB0_115
.Lw_last_nv:
	s_waitcnt vmcnt(11)
	ds_write_b128 v180, v[130:133]
	s_waitcnt vmcnt(10)
	ds_write_b128 v180, v[134:137] offset:10240
	s_waitcnt vmcnt(9)
	ds_write_b128 v180, v[150:153] offset:25600
	s_waitcnt vmcnt(8)
	ds_write_b128 v180, v[138:141] offset:5120
	s_waitcnt vmcnt(7)
	ds_write_b128 v180, v[142:145] offset:15360
	s_waitcnt vmcnt(6)
	ds_write_b128 v180, v[154:157] offset:30720
	s_waitcnt vmcnt(5)
	ds_write_b128 v180, v[146:149] offset:20480
	s_waitcnt vmcnt(4)
	ds_write_b128 v180, v[158:161] offset:35840
	s_waitcnt vmcnt(3)
	ds_write_b128 v180, v[162:165] offset:40960
	s_waitcnt vmcnt(2)
	ds_write_b128 v180, v[166:169] offset:51200
	s_waitcnt vmcnt(1)
	ds_write_b128 v180, v[170:173] offset:46080
	s_waitcnt vmcnt(0)
	ds_write_b128 v180, v[174:177] offset:56320
	s_waitcnt lgkmcnt(0)
	s_barrier
	s_branch .LBB0_115

; DI void attn_item_A(const Params& p, int layer, int b, int head, int qb, u16* sm, float lam, float lam_init, int wv) {
;     ...
;   const int t7 = tid & 127, wp = t7 >> 6;
;   const int csrc = (lane & 7) ^ ((4 * wp + (lane >> 4)) & 7);
;   const int row0 = wp * 8 + (lane >> 3);
;   const u16* kg = projb + koff + csrc * 8;
;   const u16* vg = p.vt + ((size_t)(b * NVH + vh) * 64) * SEQ + csrc * 8;
;   float zf = 0.f;
;   asm volatile("" : "+v"(zf));
;   f32x16 o[2][2];
; #pragma unroll
;   for (int a = 0; a < 2; ++a)
; #pragma unroll
;     for (int d = 0; d < 2; ++d)
; #pragma unroll
;       for (int e = 0; e < 16; ++e) o[a][d][e] = zf;
;   float m0 = 0.f, m1 = 0.f;
;   f32x4 ls0 = {zf, zf, zf, zf}, ls1 = {zf, zf, zf, zf};
;   const bf16x8 ones = rowsum_ones(lane);
;   bool started = false;
;   const int npairs = (qb >> 1) + 1;
;   const int T0 = 2 * (npairs - 1) + kh;
;   const bool v0 = (T0 <= qb);
;   auto dma_tile = [&](int T, int c) {
;     const int k0 = 64 * T;
;     u16* Kd = Kb0 + c * (2 * 64 * 64) + wp * (8 * 64);
; #pragma unroll
;     for (int i = 0; i < 4; ++i) {
;       __builtin_amdgcn_global_load_lds((const unsigned*)(kg + (size_t)(k0 + row0 + 16 * i) * DIN), (unsigned*)(Kd + i * 16 * 64), 16, 0, 0);
;       __builtin_amdgcn_global_load_lds((const unsigned*)(vg + (size_t)(row0 + 16 * i) * SEQ + k0), (unsigned*)(Kd + 64 * 64 + i * 16 * 64), 16, 0, 0);
;     }
;   };
.LBB0_276:
	s_or_b64 exec, exec, s[18:19]
	s_waitcnt vmcnt(0)
	v_and_b32_e32 v205, 60, v125
	s_waitcnt vmcnt(0) lgkmcnt(0)
	s_barrier
	s_and_saveexec_b64 s[18:19], vcc
	s_cbranch_execz .LBB0_292
	v_add_u32_e32 v66, v120, v171
	v_sub_u32_e32 v66, v66, v124
	v_lshlrev_b32_e32 v67, 6, v118
	v_sub_u32_e32 v66, v66, v67
	v_lshlrev_b32_e32 v206, 6, v173
	v_lshlrev_b32_e32 v67, 6, v119
	v_sub_u32_e32 v66, v66, v206
	v_and_b32_e32 v67, 0xffffff80, v67
	v_sub_u32_e32 v66, v66, v67
	v_add_u32_e32 v207, 0x2040, v66
	v_add_u32_e32 v66, v118, v173
	s_movk_i32 s2, 0xff7f
	v_add3_u32 v208, v66, v123, s2
	v_or_b32_e32 v66, v121, v67
	v_cmp_gt_u32_e64 s[36:37], 16, v171
	v_add_u32_e32 v209, v66, v122
	v_add_u32_e32 v210, 0xffffff00, v67
	v_add_u32_e32 v72, v206, v209
	v_add_u32_e32 v68, 0xffffff00, v72
	v_mad_i64_i32 v[68:69], s[38:39], v68, s8, v[160:161]
	v_readlane_b32 s22, v250, 19
	v_add_u32_e32 v66, v206, v210
	v_ashrrev_i32_e32 v67, 31, v66
	v_lshl_add_u64 v[68:69], v[68:69], 0, s[68:69]
	v_lshlrev_b64 v[66:67], 1, v[66:67]
	v_or_b32_e32 v74, v121, v122
	v_subrev_u32_e32 v75, s22, v160
	v_lshl_add_u64 v[70:71], v[162:163], 0, v[66:67]
	v_mul_u32_u24_e32 v76, 0x1a00, v74
	v_lshlrev_b32_e32 v77, 14, v74
	v_add_u32_e32 v76, v76, v75
	v_add_u32_e32 v77, v77, v75
	v_sub_co_u32_e32 v68, vcc, v68, v76
	s_nop 1
	v_subbrev_co_u32_e32 v69, vcc, 0, v69, vcc
	v_sub_co_u32_e32 v70, vcc, v70, v77
	s_nop 1
	v_subbrev_co_u32_e32 v71, vcc, 0, v71, vcc
	v_mov_b32_e32 v160, v76
	v_readfirstlane_b32 s98, v68
	v_readfirstlane_b32 s99, v69
	v_readfirstlane_b32 s100, v70
	v_readfirstlane_b32 s101, v71
	v_readfirstlane_b32 s87, v177
	v_add_u32_e32 v161, 0x1a000, v76
	v_add_u32_e32 v162, 0x34000, v76
	v_add_u32_e32 v163, 0x4e000, v76
	v_mov_b32_e32 v164, v77
	v_add_u32_e32 v165, 0x40000, v77
	v_add_u32_e32 v166, 0x80000, v77
	v_add_u32_e32 v167, 0xc0000, v77
	s_movk_i32 s64, 0x2000
	s_mov_b32 s65, 0
	s_mov_b64 s[40:41], 0
	s_mov_b64 s[42:43], s[4:5]
	s_branch .LBB0_279
	s_nop 0
	s_nop 0
	s_nop 0
	s_nop 0
	s_nop 0
	s_nop 0
	s_nop 0
	s_nop 0
